# ret_kv: 64 two-byte stores per item replaced by chunked wave-private LDS transposition + 8 coalesced dwordx4 stores
# speedup vs baseline: 1.0031x; 1.0031x over previous
.LBB0_691:
	s_or_b64 exec, exec, s[0:1]
	v_lshrrev_b32_e32 v200, 3, v67
	v_mul_u32_u24_e32 v201, v4, v200
	v_and_b32_e32 v202, 7, v67
	v_lshlrev_b32_e32 v201, 1, v201
	v_lshlrev_b32_e32 v202, 4, v202
	v_lshl_add_u32 v201, v6, 1, v201
	v_add_u32_e32 v202, v201, v202
	v_mov_b32_e32 v203, 0
	v_lshl_add_u64 v[204:205], v[0:1], 0, v[202:203]
	v_lshl_add_u64 v[206:207], v[2:3], 0, v[202:203]
	v_lshlrev_b32_e32 v208, 6, v4
	v_mov_b32_e32 v209, 0
	global_load_dwordx4 v[160:163], v[204:205], off
	global_load_dwordx4 v[176:179], v[206:207], off
	v_lshl_add_u64 v[204:205], v[204:205], 0, v[208:209]
	v_lshl_add_u64 v[206:207], v[206:207], 0, v[208:209]
	global_load_dwordx4 v[164:167], v[204:205], off
	global_load_dwordx4 v[180:183], v[206:207], off
	v_lshl_add_u64 v[204:205], v[204:205], 0, v[208:209]
	v_lshl_add_u64 v[206:207], v[206:207], 0, v[208:209]
	global_load_dwordx4 v[168:171], v[204:205], off
	global_load_dwordx4 v[184:187], v[206:207], off
	v_lshl_add_u64 v[204:205], v[204:205], 0, v[208:209]
	v_lshl_add_u64 v[206:207], v[206:207], 0, v[208:209]
	global_load_dwordx4 v[172:175], v[204:205], off
	global_load_dwordx4 v[188:191], v[206:207], off
	s_mul_i32 s99, s98, 0x9000
	v_mul_u32_u24_e32 v212, 0x14000, v150
	v_add_u32_e32 v212, s99, v212
	v_mul_u32_u24_e32 v210, 0x90, v200
	v_and_b32_e32 v211, 7, v67
	v_lshl_add_u32 v210, v211, 4, v210
	v_add_u32_e32 v210, v210, v212
	v_and_b32_e32 v213, 0x5f, v67
	v_mul_u32_u24_e32 v213, 0x90, v213
	v_bfe_u32 v211, v67, 5, 1
	v_lshl_add_u32 v213, v211, 4, v213
	v_add_u32_e32 v213, v213, v212
	v_ashrrev_i32_e32 v214, 1, v67
	v_and_b32_e32 v214, 0xffc0, v214
	v_and_b32_e32 v215, 31, v67
	v_or_b32_e32 v214, v214, v215
	v_mul_u32_u24_e32 v214, 0x90, v214
	v_lshl_add_u32 v214, v211, 4, v214
	v_add_u32_e32 v214, v214, v212
	v_add_u32_e32 v214, 0x4800, v214
	s_waitcnt vmcnt(0)
	ds_write_b128 v210, v[160:163]
	ds_write_b128 v210, v[164:167] offset:4608
	ds_write_b128 v210, v[168:171] offset:9216
	ds_write_b128 v210, v[172:175] offset:13824
	ds_write_b128 v210, v[176:179] offset:18432
	ds_write_b128 v210, v[180:183] offset:23040
	ds_write_b128 v210, v[184:187] offset:27648
	ds_write_b128 v210, v[188:191] offset:32256
	s_waitcnt lgkmcnt(0)
	s_barrier
	v_and_b32_e32 v18, 0x5f, v67
	v_and_b32_e32 v5, 31, v67
	v_ashrrev_i32_e32 v10, 1, v67
	v_mul_u32_u24_e32 v7, v4, v18
	v_lshlrev_b32_e32 v64, 1, v7
	v_and_or_b32 v102, v10, s3, v5
	v_bfe_u32 v71, v67, 5, 1
	v_lshl_add_u64 v[8:9], v[0:1], 0, v[64:65]
	v_lshlrev_b32_e32 v64, 1, v6
	v_or_b32_e32 v66, 32, v102
	v_lshl_add_u64 v[6:7], v[8:9], 0, v[64:65]
	v_lshlrev_b32_e32 v14, 4, v71
	v_mov_b32_e32 v15, v65
	v_mad_i64_i32 v[10:11], s[0:1], v4, v102, 0
	v_mad_i64_i32 v[16:17], s[0:1], v4, v66, 0
	v_lshl_add_u64 v[92:93], v[6:7], 0, v[14:15]
	v_lshl_add_u64 v[10:11], v[10:11], 1, v[2:3]
	v_lshl_add_u64 v[2:3], v[16:17], 1, v[2:3]
	ds_read_b128 v[6:9], v213
	v_lshl_add_u64 v[2:3], v[2:3], 0, v[64:65]
	v_lshl_add_u64 v[96:97], v[2:3], 0, v[14:15]
	v_or_b32_e32 v2, 32, v18
	v_lshl_add_u64 v[10:11], v[10:11], 0, v[64:65]
	v_mul_u32_u24_e32 v2, v4, v2
	v_lshl_add_u64 v[94:95], v[10:11], 0, v[14:15]
	v_mov_b32_e32 v3, v65
	v_lshlrev_b32_e32 v2, 1, v2
	ds_read_b128 v[10:13], v214
	ds_read_b128 v[72:75], v214 offset:4608
	v_lshl_add_u64 v[0:1], v[0:1], 0, v[2:3]
	v_lshl_add_u64 v[0:1], v[0:1], 0, v[64:65]
	v_lshl_add_u64 v[100:101], v[0:1], 0, v[14:15]
	ds_read_b128 v[76:79], v213 offset:32
	ds_read_b128 v[80:83], v214 offset:32
	ds_read_b128 v[0:3], v213 offset:4608
	ds_read_b128 v[84:87], v214 offset:4640
	ds_read_b128 v[88:91], v213 offset:4640
	v_lshlrev_b32_e32 v64, 7, v67
	v_and_b32_e32 v64, 0x2000, v64
	v_ashrrev_i32_e32 v69, 31, v68
	v_lshl_or_b32 v64, v71, 9, v64
	v_lshlrev_b64 v[68:69], 15, v[68:69]
	v_or_b32_e32 v71, 0x800, v64
	v_or_b32_e32 v103, 0x880, v64
	v_or_b32_e32 v104, 0x900, v64
	v_or_b32_e32 v105, 0x980, v64
	v_or_b32_e32 v106, 0xc00, v64
	v_or_b32_e32 v107, 0xc80, v64
	v_lshl_add_u64 v[68:69], s[88:89], 0, v[68:69]
	v_ashrrev_i32_e32 v67, 31, v66
	v_add_u32_e32 v70, 0x8000, v70
	s_waitcnt lgkmcnt(6)
	v_mfma_f32_32x32x16_bf16 v[48:63], v[6:9], v[10:13], 0
	s_waitcnt lgkmcnt(5)
	v_mfma_f32_32x32x16_bf16 v[32:47], v[6:9], v[72:75], 0
	s_waitcnt lgkmcnt(2)
	v_mfma_f32_32x32x16_bf16 v[16:31], v[0:3], v[10:13], 0
	v_mfma_f32_32x32x16_bf16 v[0:15], v[0:3], v[72:75], 0
	ds_read_b128 v[72:75], v213 offset:64
	v_mfma_f32_32x32x16_bf16 v[48:63], v[76:79], v[80:83], v[48:63]
	s_waitcnt lgkmcnt(2)
	v_mfma_f32_32x32x16_bf16 v[32:47], v[76:79], v[84:87], v[32:47]
	ds_read_b128 v[76:79], v214 offset:64
	s_waitcnt lgkmcnt(2)
	v_mfma_f32_32x32x16_bf16 v[16:31], v[88:91], v[80:83], v[16:31]
	v_mfma_f32_32x32x16_bf16 v[0:15], v[88:91], v[84:87], v[0:15]
	ds_read_b128 v[80:83], v214 offset:4672
	ds_read_b128 v[84:87], v213 offset:96
	ds_read_b128 v[88:91], v214 offset:96
	s_nop 0
	ds_read_b128 v[92:95], v213 offset:4672
	s_nop 0
	ds_read_b128 v[96:99], v214 offset:4704
	s_waitcnt lgkmcnt(4)
	v_mfma_f32_32x32x16_bf16 v[32:47], v[72:75], v[80:83], v[32:47]
	v_mfma_f32_32x32x16_bf16 v[48:63], v[72:75], v[76:79], v[48:63]
	ds_read_b128 v[72:75], v213 offset:4704
	v_add_u32_e32 v100, v107, v102
	v_ashrrev_i32_e32 v101, 31, v100
	s_waitcnt lgkmcnt(3)
	v_mfma_f32_32x32x16_bf16 v[48:63], v[84:87], v[88:91], v[48:63]
	s_waitcnt lgkmcnt(2)
	v_mfma_f32_32x32x16_bf16 v[16:31], v[92:95], v[76:79], v[16:31]
	v_mfma_f32_32x32x16_bf16 v[0:15], v[92:95], v[80:83], v[0:15]
	s_waitcnt lgkmcnt(1)
	v_mfma_f32_32x32x16_bf16 v[32:47], v[84:87], v[96:99], v[32:47]
	s_waitcnt lgkmcnt(0)
	v_mfma_f32_32x32x16_bf16 v[16:31], v[72:75], v[88:91], v[16:31]
	v_mfma_f32_32x32x16_bf16 v[0:15], v[72:75], v[96:99], v[0:15]
	v_and_b32_e32 v216, 63, v151
	v_lshrrev_b32_e32 v217, 6, v151
	v_and_b32_e32 v218, 31, v216
	v_lshrrev_b32_e32 v219, 5, v216
	v_mul_u32_u24_e32 v220, 0x14000, v150
	v_lshl_add_u32 v220, v217, 11, v220
	v_add_u32_e32 v220, 0x12000, v220
	v_lshlrev_b32_e32 v221, 9, v219
	v_lshl_add_u32 v221, v218, 1, v221
	v_add_u32_e32 v221, v221, v220
	v_lshl_add_u32 v222, v216, 4, v220
	v_and_b32_e32 v224, 1, v217
	v_lshlrev_b32_e32 v224, 6, v224
	v_lshrrev_b32_e32 v223, 3, v216
	v_add_u32_e32 v224, v224, v223
	v_lshlrev_b32_e32 v224, 8, v224
	v_lshrrev_b32_e32 v223, 1, v217
	v_lshl_add_u32 v224, v223, 7, v224
	v_and_b32_e32 v223, 7, v216
	v_lshl_add_u32 v224, v223, 4, v224
	v_mov_b32_e32 v225, 0
	v_lshl_add_u64 v[226:227], v[68:69], 0, v[224:225]
	v_mov_b32_e32 v208, 0x800
	v_mov_b32_e32 v209, 0
	s_nop 7
	v_cvt_pk_bf16_f32 v176, v48, s0
	ds_write_b16 v221, v176
	v_cvt_pk_bf16_f32 v177, v49, s0
	ds_write_b16 v221, v177 offset:128
	v_cvt_pk_bf16_f32 v178, v50, s0
	ds_write_b16 v221, v178 offset:256
	v_cvt_pk_bf16_f32 v179, v51, s0
	ds_write_b16 v221, v179 offset:384
	v_cvt_pk_bf16_f32 v180, v32, s0
	ds_write_b16 v221, v180 offset:64
	v_cvt_pk_bf16_f32 v181, v33, s0
	ds_write_b16 v221, v181 offset:192
	v_cvt_pk_bf16_f32 v182, v34, s0
	ds_write_b16 v221, v182 offset:320
	v_cvt_pk_bf16_f32 v183, v35, s0
	ds_write_b16 v221, v183 offset:448
	s_waitcnt lgkmcnt(0)
	ds_read_b128 v[200:203], v222
	v_cvt_pk_bf16_f32 v176, v52, s0
	ds_write_b16 v221, v176 offset:1024
	v_cvt_pk_bf16_f32 v177, v53, s0
	ds_write_b16 v221, v177 offset:1152
	v_cvt_pk_bf16_f32 v178, v54, s0
	ds_write_b16 v221, v178 offset:1280
	v_cvt_pk_bf16_f32 v179, v55, s0
	ds_write_b16 v221, v179 offset:1408
	v_cvt_pk_bf16_f32 v180, v36, s0
	ds_write_b16 v221, v180 offset:1088
	v_cvt_pk_bf16_f32 v181, v37, s0
	ds_write_b16 v221, v181 offset:1216
	v_cvt_pk_bf16_f32 v182, v38, s0
	ds_write_b16 v221, v182 offset:1344
	v_cvt_pk_bf16_f32 v183, v39, s0
	ds_write_b16 v221, v183 offset:1472
	s_waitcnt lgkmcnt(0)
	ds_read_b128 v[204:207], v222 offset:1024
	global_store_dwordx4 v[226:227], v[200:203], off
	v_lshl_add_u64 v[226:227], v[226:227], 0, v[208:209]
	v_cvt_pk_bf16_f32 v176, v56, s0
	ds_write_b16 v221, v176
	v_cvt_pk_bf16_f32 v177, v57, s0
	ds_write_b16 v221, v177 offset:128
	v_cvt_pk_bf16_f32 v178, v58, s0
	ds_write_b16 v221, v178 offset:256
	v_cvt_pk_bf16_f32 v179, v59, s0
	ds_write_b16 v221, v179 offset:384
	v_cvt_pk_bf16_f32 v180, v40, s0
	ds_write_b16 v221, v180 offset:64
	v_cvt_pk_bf16_f32 v181, v41, s0
	ds_write_b16 v221, v181 offset:192
	v_cvt_pk_bf16_f32 v182, v42, s0
	ds_write_b16 v221, v182 offset:320
	v_cvt_pk_bf16_f32 v183, v43, s0
	ds_write_b16 v221, v183 offset:448
	s_waitcnt lgkmcnt(0)
	ds_read_b128 v[200:203], v222
	global_store_dwordx4 v[226:227], v[204:207], off
	v_lshl_add_u64 v[226:227], v[226:227], 0, v[208:209]
	v_cvt_pk_bf16_f32 v176, v60, s0
	ds_write_b16 v221, v176 offset:1024
	v_cvt_pk_bf16_f32 v177, v61, s0
	ds_write_b16 v221, v177 offset:1152
	v_cvt_pk_bf16_f32 v178, v62, s0
	ds_write_b16 v221, v178 offset:1280
	v_cvt_pk_bf16_f32 v179, v63, s0
	ds_write_b16 v221, v179 offset:1408
	v_cvt_pk_bf16_f32 v180, v44, s0
	ds_write_b16 v221, v180 offset:1088
	v_cvt_pk_bf16_f32 v181, v45, s0
	ds_write_b16 v221, v181 offset:1216
	v_cvt_pk_bf16_f32 v182, v46, s0
	ds_write_b16 v221, v182 offset:1344
	v_cvt_pk_bf16_f32 v183, v47, s0
	ds_write_b16 v221, v183 offset:1472
	s_waitcnt lgkmcnt(0)
	ds_read_b128 v[204:207], v222 offset:1024
	global_store_dwordx4 v[226:227], v[200:203], off
	v_lshl_add_u64 v[226:227], v[226:227], 0, v[208:209]
	v_cvt_pk_bf16_f32 v176, v16, s0
	ds_write_b16 v221, v176
	v_cvt_pk_bf16_f32 v177, v17, s0
	ds_write_b16 v221, v177 offset:128
	v_cvt_pk_bf16_f32 v178, v18, s0
	ds_write_b16 v221, v178 offset:256
	v_cvt_pk_bf16_f32 v179, v19, s0
	ds_write_b16 v221, v179 offset:384
	v_cvt_pk_bf16_f32 v180, v0, s0
	ds_write_b16 v221, v180 offset:64
	v_cvt_pk_bf16_f32 v181, v1, s0
	ds_write_b16 v221, v181 offset:192
	v_cvt_pk_bf16_f32 v182, v2, s0
	ds_write_b16 v221, v182 offset:320
	v_cvt_pk_bf16_f32 v183, v3, s0
	ds_write_b16 v221, v183 offset:448
	s_waitcnt lgkmcnt(0)
	ds_read_b128 v[200:203], v222
	global_store_dwordx4 v[226:227], v[204:207], off
	v_lshl_add_u64 v[226:227], v[226:227], 0, v[208:209]
	v_cvt_pk_bf16_f32 v176, v20, s0
	ds_write_b16 v221, v176 offset:1024
	v_cvt_pk_bf16_f32 v177, v21, s0
	ds_write_b16 v221, v177 offset:1152
	v_cvt_pk_bf16_f32 v178, v22, s0
	ds_write_b16 v221, v178 offset:1280
	v_cvt_pk_bf16_f32 v179, v23, s0
	ds_write_b16 v221, v179 offset:1408
	v_cvt_pk_bf16_f32 v180, v4, s0
	ds_write_b16 v221, v180 offset:1088
	v_cvt_pk_bf16_f32 v181, v5, s0
	ds_write_b16 v221, v181 offset:1216
	v_cvt_pk_bf16_f32 v182, v6, s0
	ds_write_b16 v221, v182 offset:1344
	v_cvt_pk_bf16_f32 v183, v7, s0
	ds_write_b16 v221, v183 offset:1472
	s_waitcnt lgkmcnt(0)
	ds_read_b128 v[204:207], v222 offset:1024
	global_store_dwordx4 v[226:227], v[200:203], off
	v_lshl_add_u64 v[226:227], v[226:227], 0, v[208:209]
	v_cvt_pk_bf16_f32 v176, v24, s0
	ds_write_b16 v221, v176
	v_cvt_pk_bf16_f32 v177, v25, s0
	ds_write_b16 v221, v177 offset:128
	v_cvt_pk_bf16_f32 v178, v26, s0
	ds_write_b16 v221, v178 offset:256
	v_cvt_pk_bf16_f32 v179, v27, s0
	ds_write_b16 v221, v179 offset:384
	v_cvt_pk_bf16_f32 v180, v8, s0
	ds_write_b16 v221, v180 offset:64
	v_cvt_pk_bf16_f32 v181, v9, s0
	ds_write_b16 v221, v181 offset:192
	v_cvt_pk_bf16_f32 v182, v10, s0
	ds_write_b16 v221, v182 offset:320
	v_cvt_pk_bf16_f32 v183, v11, s0
	ds_write_b16 v221, v183 offset:448
	s_waitcnt lgkmcnt(0)
	ds_read_b128 v[200:203], v222
	global_store_dwordx4 v[226:227], v[204:207], off
	v_lshl_add_u64 v[226:227], v[226:227], 0, v[208:209]
	v_cvt_pk_bf16_f32 v176, v28, s0
	ds_write_b16 v221, v176 offset:1024
	v_cvt_pk_bf16_f32 v177, v29, s0
	ds_write_b16 v221, v177 offset:1152
	v_cvt_pk_bf16_f32 v178, v30, s0
	ds_write_b16 v221, v178 offset:1280
	v_cvt_pk_bf16_f32 v179, v31, s0
	ds_write_b16 v221, v179 offset:1408
	v_cvt_pk_bf16_f32 v180, v12, s0
	ds_write_b16 v221, v180 offset:1088
	v_cvt_pk_bf16_f32 v181, v13, s0
	ds_write_b16 v221, v181 offset:1216
	v_cvt_pk_bf16_f32 v182, v14, s0
	ds_write_b16 v221, v182 offset:1344
	v_cvt_pk_bf16_f32 v183, v15, s0
	ds_write_b16 v221, v183 offset:1472
	s_waitcnt lgkmcnt(0)
	ds_read_b128 v[204:207], v222 offset:1024
	global_store_dwordx4 v[226:227], v[200:203], off
	v_lshl_add_u64 v[226:227], v[226:227], 0, v[208:209]
	s_waitcnt lgkmcnt(0)
	global_store_dwordx4 v[226:227], v[204:207], off
	s_add_i32 s0, s4, 0x200
	s_xor_b32 s98, s98, 1
	s_cmpk_gt_i32 s4, 0x61f
	s_mov_b32 s4, s0
	s_cbranch_scc1 .LBB0_696
